# fft1/fft2 DFT-table fragment reads double-buffered with a free quad (92 read-wait-MFMA triples), on top of the fourth combination
# baseline (speedup 1.0000x reference)
; __device__ __forceinline__ f32x4 mfma16(bf16x8 a, bf16x8 b, f32x4 c) { return mfma16_g(a, b, c); }
; __device__ __forceinline__ void fft1_phase_wave(const Ctx& c, unsigned char* lds_raw) {
;     ...
;         for (int n = 0; n < 4; ++n) {
;             f32x4 wre[4], wim[4];
; #pragma unroll
;             for (int m = 0; m < 4; ++m) { wre[m] = (f32x4){0.f, 0.f, 0.f, 0.f}; wim[m] = wre[m]; }
; #pragma unroll
;             for (int ks = 0; ks < 2; ++ks) {
;                 const bf16x8 cb = FT_B(ks, n, 0), sb = FT_B(ks, n, 1);
; #pragma unroll
;                 for (int m = 0; m < 4; ++m) { wre[m] = mfma16(ua[m][ks], cb, wre[m]); wim[m] = mfma16(ua[m][ks], sb, wim[m]); }
;                 __builtin_amdgcn_sched_barrier(0);
;             }
;             asm volatile("s_nop 15\n\ts_nop 15" : "+v"(wre[0]), "+v"(wre[1]), "+v"(wre[2]), "+v"(wre[3]), "+v"(wim[0]), "+v"(wim[1]), "+v"(wim[2]), "+v"(wim[3]));
;             bf16x8 bre[2], bim[2];
; #pragma unroll
;             for (int ks = 0; ks < 2; ++ks) { bre[ks] = pack8(wre[2 * ks], wre[2 * ks + 1]); bim[ks] = pack8(wim[2 * ks], wim[2 * ks + 1]); }
;             asm volatile("s_nop 7" : "+v"(bre[0]), "+v"(bre[1]), "+v"(bim[0]), "+v"(bim[1]));
; #pragma unroll
;             for (int mp = 0; mp < 2; ++mp) {
;                 f32x4 yre[2], yin[2];
; #pragma unroll
;                 for (int q = 0; q < 2; ++q) { yre[q] = (f32x4){0.f, 0.f, 0.f, 0.f}; yin[q] = yre[q]; }
; #pragma unroll
;                 for (int ks = 0; ks < 2; ++ks) {
; #pragma unroll
;                     for (int q = 0; q < 2; ++q) { const bf16x8 ca = FT_A(2 * mp + q, ks, 0); yre[q] = mfma16(bre[ks], ca, yre[q]); yin[q] = mfma16(bim[ks], ca, yin[q]); }
;                     __builtin_amdgcn_sched_barrier(0);
; #pragma unroll
;                     for (int q = 0; q < 2; ++q) { yre[q] = mfma16(bim[ks], FT_A(2 * mp + q, ks, 2), yre[q]); yin[q] = mfma16(bre[ks], FT_A(2 * mp + q, ks, 1), yin[q]); }
;                     __builtin_amdgcn_sched_barrier(0);
;                 }
;                 asm volatile("s_nop 15\n\ts_nop 15" : "+v"(yre[0]), "+v"(yin[0]), "+v"(yre[1]), "+v"(yin[1]));
; #pragma unroll
;                 for (int q = 0; q < 2; ++q) {
;                     const int k1 = 16 * (2 * mp + q) + fr;
;                     const float2 tw = twv[mp][q];
;                     u32x4 wv;
; #pragma unroll
.LBB0_1105:
	ds_read_b128 v[78:81], v44
	ds_read_b128 v[82:85], v44 offset:1024
	s_waitcnt lgkmcnt(1)
	v_mfma_f32_16x16x32_bf16 v[86:89], v[2:5], v[78:81], 0
	s_waitcnt lgkmcnt(0)
	v_mfma_f32_16x16x32_bf16 v[90:93], v[2:5], v[82:85], 0
	v_mfma_f32_16x16x32_bf16 v[94:97], v[10:13], v[78:81], 0
	v_mfma_f32_16x16x32_bf16 v[98:101], v[10:13], v[82:85], 0
	v_mfma_f32_16x16x32_bf16 v[102:105], v[18:21], v[78:81], 0
	v_mfma_f32_16x16x32_bf16 v[106:109], v[18:21], v[82:85], 0
	v_mfma_f32_16x16x32_bf16 v[110:113], v[26:29], v[78:81], 0
	v_mfma_f32_16x16x32_bf16 v[78:81], v[26:29], v[82:85], 0
	ds_read_b128 v[82:85], v44 offset:8192
	ds_read_b128 v[114:117], v44 offset:9216
	s_waitcnt lgkmcnt(1)
	v_mfma_f32_16x16x32_bf16 v[86:89], v[6:9], v[82:85], v[86:89]
	s_waitcnt lgkmcnt(0)
	v_mfma_f32_16x16x32_bf16 v[90:93], v[6:9], v[114:117], v[90:93]
	v_mfma_f32_16x16x32_bf16 v[94:97], v[14:17], v[82:85], v[94:97]
	v_mfma_f32_16x16x32_bf16 v[98:101], v[14:17], v[114:117], v[98:101]
	v_mfma_f32_16x16x32_bf16 v[102:105], v[22:25], v[82:85], v[102:105]
	v_mfma_f32_16x16x32_bf16 v[106:109], v[22:25], v[114:117], v[106:109]
	v_mfma_f32_16x16x32_bf16 v[110:113], v[30:33], v[82:85], v[110:113]
	v_mfma_f32_16x16x32_bf16 v[78:81], v[30:33], v[114:117], v[78:81]
	s_nop 15
	s_nop 15
	s_nop 0
	v_cvt_pk_bf16_f32 v82, v86, v87
	v_cvt_pk_bf16_f32 v83, v88, v89
	v_cvt_pk_bf16_f32 v84, v94, v95
	v_cvt_pk_bf16_f32 v85, v96, v97
	v_cvt_pk_bf16_f32 v86, v90, v91
	v_cvt_pk_bf16_f32 v87, v92, v93
	v_cvt_pk_bf16_f32 v88, v98, v99
	v_cvt_pk_bf16_f32 v89, v100, v101
	v_cvt_pk_bf16_f32 v90, v102, v103
	v_cvt_pk_bf16_f32 v91, v104, v105
	v_cvt_pk_bf16_f32 v92, v110, v111
	v_cvt_pk_bf16_f32 v93, v112, v113
	v_cvt_pk_bf16_f32 v94, v106, v107
	v_cvt_pk_bf16_f32 v95, v108, v109
	v_cvt_pk_bf16_f32 v96, v78, v79
	v_cvt_pk_bf16_f32 v97, v80, v81
	s_nop 7
	ds_read_b128 v[78:81], v72 offset:16384
	ds_read_b128 v[240:243], v72 offset:22528
	s_waitcnt lgkmcnt(1)
	v_mfma_f32_16x16x32_bf16 v[98:101], v[82:85], v[78:81], 0
	v_mfma_f32_16x16x32_bf16 v[102:105], v[86:89], v[78:81], 0
	ds_read_b128 v[78:81], v72 offset:18432
	s_waitcnt lgkmcnt(1)
	v_mfma_f32_16x16x32_bf16 v[106:109], v[82:85], v[240:243], 0
	v_mfma_f32_16x16x32_bf16 v[110:113], v[86:89], v[240:243], 0
	ds_read_b128 v[240:243], v72 offset:17408
	s_waitcnt lgkmcnt(1)
	v_mfma_f32_16x16x32_bf16 v[98:101], v[86:89], v[78:81], v[98:101]
	ds_read_b128 v[78:81], v72 offset:24576
	s_waitcnt lgkmcnt(1)
	v_mfma_f32_16x16x32_bf16 v[102:105], v[82:85], v[240:243], v[102:105]
	ds_read_b128 v[240:243], v72 offset:23552
	s_waitcnt lgkmcnt(1)
	v_mfma_f32_16x16x32_bf16 v[106:109], v[86:89], v[78:81], v[106:109]
	ds_read_b128 v[78:81], v72 offset:19456
	s_waitcnt lgkmcnt(1)
	v_mfma_f32_16x16x32_bf16 v[110:113], v[82:85], v[240:243], v[110:113]
	ds_read_b128 v[240:243], v72 offset:25600
	s_waitcnt lgkmcnt(1)
	v_mfma_f32_16x16x32_bf16 v[98:101], v[90:93], v[78:81], v[98:101]
	v_mfma_f32_16x16x32_bf16 v[102:105], v[94:97], v[78:81], v[102:105]
	ds_read_b128 v[78:81], v72 offset:21504
	s_waitcnt lgkmcnt(1)
	v_mfma_f32_16x16x32_bf16 v[106:109], v[90:93], v[240:243], v[106:109]
	v_mfma_f32_16x16x32_bf16 v[110:113], v[94:97], v[240:243], v[110:113]
	ds_read_b128 v[240:243], v72 offset:20480
	s_waitcnt lgkmcnt(1)
	v_mfma_f32_16x16x32_bf16 v[98:101], v[94:97], v[78:81], v[98:101]
	ds_read_b128 v[78:81], v72 offset:27648
	s_waitcnt lgkmcnt(1)
	v_mfma_f32_16x16x32_bf16 v[102:105], v[90:93], v[240:243], v[102:105]
	ds_read_b128 v[240:243], v72 offset:26624
	s_waitcnt lgkmcnt(1)
	v_mfma_f32_16x16x32_bf16 v[106:109], v[94:97], v[78:81], v[106:109]
	s_waitcnt lgkmcnt(0)
	v_mfma_f32_16x16x32_bf16 v[110:113], v[90:93], v[240:243], v[110:113]
	s_nop 15
	s_nop 15
	s_nop 1
	v_mov_b32_e32 v80, v102
	v_mov_b32_e32 v81, v98
	v_xor_b32_e32 v79, 0x80000000, v102
	v_mov_b32_e32 v78, v98
	v_pk_mul_f32 v[80:81], v[64:65], v[80:81]
	v_mov_b32_e32 v98, v103
	v_pk_fma_f32 v[78:79], v[56:57], v[78:79], v[80:81] neg_lo:[0,0,1] neg_hi:[0,0,1]
	v_xor_b32_e32 v81, 0x80000000, v103
	v_mov_b32_e32 v80, v99
	v_pk_mul_f32 v[98:99], v[64:65], v[98:99]
	v_cvt_pk_bf16_f32 v78, v78, v79
	v_pk_fma_f32 v[80:81], v[56:57], v[80:81], v[98:99] neg_lo:[0,0,1] neg_hi:[0,0,1]
	v_mov_b32_e32 v98, v104
	v_mov_b32_e32 v99, v100
	v_cvt_pk_bf16_f32 v79, v80, v81
	v_xor_b32_e32 v81, 0x80000000, v104
	v_mov_b32_e32 v80, v100
	v_pk_mul_f32 v[98:99], v[64:65], v[98:99]
	v_mov_b32_e32 v100, v105
	v_pk_fma_f32 v[80:81], v[56:57], v[80:81], v[98:99] neg_lo:[0,0,1] neg_hi:[0,0,1]
	v_xor_b32_e32 v99, 0x80000000, v105
	v_mov_b32_e32 v98, v101
	v_pk_mul_f32 v[100:101], v[64:65], v[100:101]
	v_cvt_pk_bf16_f32 v80, v80, v81
	v_pk_fma_f32 v[98:99], v[56:57], v[98:99], v[100:101] neg_lo:[0,0,1] neg_hi:[0,0,1]
	v_xor_b32_e32 v103, 0x80000000, v113
	v_cvt_pk_bf16_f32 v81, v98, v99
	v_lshl_add_u64 v[98:99], v[54:55], 0, s[0:1]
	global_store_dwordx4 v[98:99], v[78:81], off
	v_mov_b32_e32 v102, v109
	s_nop 0
	v_mov_b32_e32 v80, v110
	v_mov_b32_e32 v81, v106
	v_xor_b32_e32 v79, 0x80000000, v110
	v_mov_b32_e32 v78, v106
	v_pk_mul_f32 v[80:81], v[66:67], v[80:81]
	v_mov_b32_e32 v106, v111
	v_pk_fma_f32 v[78:79], v[58:59], v[78:79], v[80:81] neg_lo:[0,0,1] neg_hi:[0,0,1]
	v_xor_b32_e32 v81, 0x80000000, v111
	v_mov_b32_e32 v80, v107
	v_pk_mul_f32 v[98:99], v[66:67], v[106:107]
	v_cvt_pk_bf16_f32 v78, v78, v79
	v_pk_fma_f32 v[80:81], v[58:59], v[80:81], v[98:99] neg_lo:[0,0,1] neg_hi:[0,0,1]
	v_mov_b32_e32 v98, v112
	v_mov_b32_e32 v99, v108
	v_cvt_pk_bf16_f32 v79, v80, v81
	v_xor_b32_e32 v81, 0x80000000, v112
	v_mov_b32_e32 v80, v108
	v_pk_mul_f32 v[98:99], v[66:67], v[98:99]
	v_mov_b32_e32 v108, v113
	v_pk_fma_f32 v[80:81], v[58:59], v[80:81], v[98:99] neg_lo:[0,0,1] neg_hi:[0,0,1]
	ds_read_b128 v[98:101], v72 offset:28672
	v_pk_mul_f32 v[104:105], v[66:67], v[108:109]
	v_cvt_pk_bf16_f32 v80, v80, v81
	v_pk_fma_f32 v[102:103], v[58:59], v[102:103], v[104:105] neg_lo:[0,0,1] neg_hi:[0,0,1]
	v_lshl_add_u64 v[106:107], v[52:53], 0, s[0:1]
	v_cvt_pk_bf16_f32 v81, v102, v103
	s_waitcnt lgkmcnt(0)
; __device__ __forceinline__ unsigned pk2(float lo, float hi) { const f32x2n v = {lo, hi}; return __builtin_bit_cast(unsigned, __builtin_convertvector(v, bf16x2n)); }
; __device__ __forceinline__ f32x4 mfma16(bf16x8 a, bf16x8 b, f32x4 c) { return mfma16_g(a, b, c); }
; __device__ __forceinline__ void fft1_phase_wave(const Ctx& c, unsigned char* lds_raw) {
;     ...
;             for (int mp = 0; mp < 2; ++mp) {
;                 f32x4 yre[2], yin[2];
; #pragma unroll
;                 for (int q = 0; q < 2; ++q) { yre[q] = (f32x4){0.f, 0.f, 0.f, 0.f}; yin[q] = yre[q]; }
; #pragma unroll
;                 for (int ks = 0; ks < 2; ++ks) {
; #pragma unroll
;                     for (int q = 0; q < 2; ++q) { const bf16x8 ca = FT_A(2 * mp + q, ks, 0); yre[q] = mfma16(bre[ks], ca, yre[q]); yin[q] = mfma16(bim[ks], ca, yin[q]); }
;                     __builtin_amdgcn_sched_barrier(0);
; #pragma unroll
;                     for (int q = 0; q < 2; ++q) { yre[q] = mfma16(bim[ks], FT_A(2 * mp + q, ks, 2), yre[q]); yin[q] = mfma16(bre[ks], FT_A(2 * mp + q, ks, 1), yin[q]); }
;                     __builtin_amdgcn_sched_barrier(0);
;                 }
;                 asm volatile("s_nop 15\n\ts_nop 15" : "+v"(yre[0]), "+v"(yin[0]), "+v"(yre[1]), "+v"(yin[1]));
; #pragma unroll
;                 for (int q = 0; q < 2; ++q) {
;                     const int k1 = 16 * (2 * mp + q) + fr;
;                     const float2 tw = twv[mp][q];
;                     u32x4 wv;
; #pragma unroll
;                     for (int rg = 0; rg < 4; ++rg) { const float yr = yre[q][rg], yi = -yin[q][rg]; wv[rg] = pk2(yr * tw.x + yi * tw.y, yi * tw.x - yr * tw.y); }
;                     *(u32x4*)(c.FY + ((size_t)(bg * 64 + k1) * 64 + s2) * 64 + 16 * n + 4 * fq) = wv;
;                 }
;             }
;         }
;     }
	v_mfma_f32_16x16x32_bf16 v[102:105], v[82:85], v[98:101], 0
	global_store_dwordx4 v[106:107], v[78:81], off
	s_nop 1
	v_mfma_f32_16x16x32_bf16 v[78:81], v[86:89], v[98:101], 0
	ds_read_b128 v[98:101], v72 offset:34816
	ds_read_b128 v[240:243], v72 offset:30720
	s_waitcnt lgkmcnt(1)
	v_mfma_f32_16x16x32_bf16 v[106:109], v[82:85], v[98:101], 0
	v_mfma_f32_16x16x32_bf16 v[110:113], v[86:89], v[98:101], 0
	ds_read_b128 v[98:101], v72 offset:29696
	s_waitcnt lgkmcnt(1)
	v_mfma_f32_16x16x32_bf16 v[102:105], v[86:89], v[240:243], v[102:105]
	ds_read_b128 v[240:243], v72 offset:36864
	s_waitcnt lgkmcnt(1)
	v_mfma_f32_16x16x32_bf16 v[78:81], v[82:85], v[98:101], v[78:81]
	s_waitcnt lgkmcnt(0)
	v_mfma_f32_16x16x32_bf16 v[106:109], v[86:89], v[240:243], v[106:109]
	ds_read_b128 v[86:89], v72 offset:35840
	s_waitcnt lgkmcnt(0)
	v_mfma_f32_16x16x32_bf16 v[98:101], v[82:85], v[86:89], v[110:113]
	ds_read_b128 v[82:85], v72 offset:31744
	ds_read_b128 v[240:243], v72 offset:37888
	s_waitcnt lgkmcnt(1)
	v_mfma_f32_16x16x32_bf16 v[86:89], v[90:93], v[82:85], v[102:105]
	v_mfma_f32_16x16x32_bf16 v[78:81], v[94:97], v[82:85], v[78:81]
	ds_read_b128 v[82:85], v72 offset:33792
	s_waitcnt lgkmcnt(1)
	v_mfma_f32_16x16x32_bf16 v[102:105], v[90:93], v[240:243], v[106:109]
	v_mfma_f32_16x16x32_bf16 v[98:101], v[94:97], v[240:243], v[98:101]
	ds_read_b128 v[240:243], v72 offset:32768
	s_waitcnt lgkmcnt(1)
	v_mfma_f32_16x16x32_bf16 v[86:89], v[94:97], v[82:85], v[86:89]
	ds_read_b128 v[82:85], v72 offset:39936
	s_waitcnt lgkmcnt(1)
	v_mfma_f32_16x16x32_bf16 v[78:81], v[90:93], v[240:243], v[78:81]
	ds_read_b128 v[240:243], v72 offset:38912
	s_waitcnt lgkmcnt(1)
	v_mfma_f32_16x16x32_bf16 v[102:105], v[94:97], v[82:85], v[102:105]
	s_waitcnt lgkmcnt(0)
	v_mfma_f32_16x16x32_bf16 v[94:97], v[90:93], v[240:243], v[98:101]
	s_nop 15
	s_nop 15
	v_lshl_add_u64 v[90:91], v[50:51], 0, s[0:1]
	s_nop 0
	v_xor_b32_e32 v83, 0x80000000, v78
	v_mov_b32_e32 v82, v86
	v_mov_b32_e32 v84, v78
	v_mov_b32_e32 v85, v86
	v_mov_b32_e32 v86, v79
	v_mov_b32_e32 v78, v88
	v_mov_b32_e32 v100, v80
	v_mov_b32_e32 v101, v88
	v_mov_b32_e32 v88, v81
	v_lshl_add_u64 v[92:93], v[48:49], 0, s[0:1]
	s_add_u32 s0, s0, 64
	v_xor_b32_e32 v99, 0x80000000, v79
	v_mov_b32_e32 v98, v87
	v_xor_b32_e32 v79, 0x80000000, v80
	v_xor_b32_e32 v107, 0x80000000, v81
	v_mov_b32_e32 v106, v89
	v_xor_b32_e32 v81, 0x80000000, v94
	v_mov_b32_e32 v80, v102
	v_mov_b32_e32 v108, v94
	v_mov_b32_e32 v109, v102
	v_xor_b32_e32 v111, 0x80000000, v95
	v_mov_b32_e32 v102, v95
	v_xor_b32_e32 v95, 0x80000000, v96
	v_mov_b32_e32 v94, v104
	v_mov_b32_e32 v112, v96
	v_mov_b32_e32 v113, v104
	v_xor_b32_e32 v115, 0x80000000, v97
	v_mov_b32_e32 v104, v97
	v_pk_mul_f32 v[84:85], v[68:69], v[84:85]
	v_pk_mul_f32 v[86:87], v[68:69], v[86:87]
	v_pk_mul_f32 v[96:97], v[68:69], v[100:101]
	v_pk_mul_f32 v[88:89], v[68:69], v[88:89]
	v_mov_b32_e32 v110, v103
	v_mov_b32_e32 v114, v105
	s_addc_u32 s1, s1, 0
	v_pk_mul_f32 v[100:101], v[70:71], v[108:109]
	v_pk_mul_f32 v[102:103], v[70:71], v[102:103]
	v_pk_mul_f32 v[108:109], v[70:71], v[112:113]
	v_pk_mul_f32 v[104:105], v[70:71], v[104:105]
	v_pk_fma_f32 v[82:83], v[60:61], v[82:83], v[84:85] neg_lo:[0,0,1] neg_hi:[0,0,1]
	v_pk_fma_f32 v[84:85], v[60:61], v[98:99], v[86:87] neg_lo:[0,0,1] neg_hi:[0,0,1]
	v_pk_fma_f32 v[86:87], v[60:61], v[78:79], v[96:97] neg_lo:[0,0,1] neg_hi:[0,0,1]
	v_pk_fma_f32 v[88:89], v[60:61], v[106:107], v[88:89] neg_lo:[0,0,1] neg_hi:[0,0,1]
	v_add_u32_e32 v44, 0x800, v44
	s_cmpk_eq_i32 s0, 0x100
	v_pk_fma_f32 v[96:97], v[62:63], v[80:81], v[100:101] neg_lo:[0,0,1] neg_hi:[0,0,1]
	v_pk_fma_f32 v[98:99], v[62:63], v[110:111], v[102:103] neg_lo:[0,0,1] neg_hi:[0,0,1]
	v_pk_fma_f32 v[94:95], v[62:63], v[94:95], v[108:109] neg_lo:[0,0,1] neg_hi:[0,0,1]
	v_pk_fma_f32 v[100:101], v[62:63], v[114:115], v[104:105] neg_lo:[0,0,1] neg_hi:[0,0,1]
	v_cvt_pk_bf16_f32 v78, v82, v83
	v_cvt_pk_bf16_f32 v79, v84, v85
	v_cvt_pk_bf16_f32 v80, v86, v87
	v_cvt_pk_bf16_f32 v81, v88, v89
	v_cvt_pk_bf16_f32 v82, v96, v97
	v_cvt_pk_bf16_f32 v83, v98, v99
	v_cvt_pk_bf16_f32 v84, v94, v95
	v_cvt_pk_bf16_f32 v85, v100, v101
	global_store_dwordx4 v[90:91], v[78:81], off
	global_store_dwordx4 v[92:93], v[82:85], off
	s_cbranch_scc0 .LBB0_1105
	s_add_i32 s6, s6, s3
	s_add_i32 s7, s7, s3
	s_cmpk_gt_i32 s6, 0x7ff
	s_cbranch_scc0 .LBB0_1102

; #define LASP __attribute__((address_space(3)))
; __device__ __forceinline__ unsigned cvtpk(float lo, float hi) { return pk2(lo, hi); }
; __device__ __forceinline__ f32x4 mfma16(bf16x8 a, bf16x8 b, f32x4 c) { return mfma16_g(a, b, c); }
; __device__ __forceinline__ void fft2_phase_mfma(const Ctx& c, int l, unsigned char* lds_raw) {
;     ...
;         for (int nn = 0; nn < 2; ++nn) {
;             bf16x8 bre[2], bim[2];
; #pragma unroll
;             for (int ks = 0; ks < 2; ++ks) {
;                 unsigned w[8];
; #pragma unroll
;                 for (int j = 0; j < 8; ++j) w[j] = wq[nn][ks][j];
;                 u32x4 re, im;
; #pragma unroll
;                 for (int e = 0; e < 4; ++e) { re[e] = (w[2 * e] & 0xffffu) | (w[2 * e + 1] << 16); im[e] = (w[2 * e] >> 16) | (w[2 * e + 1] & 0xffff0000u); }
;                 bre[ks] = __builtin_bit_cast(bf16x8, re); bim[ks] = __builtin_bit_cast(bf16x8, im);
;             }
;             f32x4 dacc[4];
; #pragma unroll
;             for (int m = 0; m < 4; ++m) dacc[m] = (f32x4){0.f, 0.f, 0.f, 0.f};
; #pragma unroll
;             for (int ks = 0; ks < 2; ++ks) {
; #pragma unroll
;                 for (int m = 0; m < 4; ++m) dacc[m] = mfma16(bre[ks], FT2(m, ks, 0), dacc[m]);
;                 __builtin_amdgcn_sched_barrier(0);
; #pragma unroll
;                 for (int m = 0; m < 4; ++m) dacc[m] = mfma16(bim[ks], FT2(m, ks, 1), dacc[m]);
;                 __builtin_amdgcn_sched_barrier(0);
;             }
;             asm volatile("s_nop 15" : "+v"(dacc[0]), "+v"(dacc[1]), "+v"(dacc[2]), "+v"(dacc[3]));
; #pragma unroll
;             for (int m = 0; m < 4; ++m) {
;                 u32x2 wv; wv.x = cvtpk(dacc[m][0] * (1.f / 512.f), dacc[m][1] * (1.f / 512.f)); wv.y = cvtpk(dacc[m][2] * (1.f / 512.f), dacc[m][3] * (1.f / 512.f));
;                 *(LASP u32x2*)(F + (16 * m + fr) * 528 + (g * 64 + 16 * (2 * nh + nn) + 4 * fq) * 2) = wv;
;             }
.LBB0_1168:
	s_waitcnt vmcnt(39)
	v_lshrrev_b32_e32 v67, 16, v99
	s_waitcnt vmcnt(37)
	v_lshrrev_b32_e32 v68, 16, v105
	s_waitcnt vmcnt(35)
	v_lshrrev_b32_e32 v69, 16, v110
	v_lshlrev_b32_e32 v66, 16, v103
	v_and_or_b32 v70, v103, s24, v67
	v_lshlrev_b32_e32 v67, 16, v107
	v_and_or_b32 v71, v107, s24, v68
	s_waitcnt vmcnt(34)
	v_lshlrev_b32_e32 v68, 16, v111
	v_and_or_b32 v72, v111, s24, v69
	s_waitcnt vmcnt(31)
	v_lshlrev_b32_e32 v69, 16, v114
	v_add_u32_e32 v157, 0, v1
	v_and_or_b32 v66, v99, s22, v66
	v_and_or_b32 v67, v105, s22, v67
	v_and_or_b32 v68, v110, s22, v68
	v_and_or_b32 v69, v112, s22, v69
	ds_read_b128 v[74:77], v157 offset:36864
	s_waitcnt vmcnt(30)
	v_lshrrev_b32_e32 v79, 16, v115
	s_waitcnt lgkmcnt(0)
	v_mfma_f32_16x16x32_bf16 v[162:165], v[66:69], v[74:77], 0
	ds_read_b128 v[74:77], v157 offset:40960
	s_waitcnt vmcnt(28)
	v_lshrrev_b32_e32 v80, 16, v118
	s_waitcnt lgkmcnt(0)
	v_mfma_f32_16x16x32_bf16 v[166:169], v[66:69], v[74:77], 0
	ds_read_b128 v[74:77], v157 offset:45056
	s_waitcnt vmcnt(23)
	v_lshrrev_b32_e32 v81, 16, v124
	s_waitcnt lgkmcnt(0)
	v_mfma_f32_16x16x32_bf16 v[170:173], v[66:69], v[74:77], 0
	ds_read_b128 v[74:77], v157 offset:49152
	v_lshrrev_b32_e32 v73, 16, v112
	v_lshlrev_b32_e32 v78, 16, v116
	v_and_or_b32 v158, v116, s24, v79
	v_lshlrev_b32_e32 v79, 16, v119
	v_and_or_b32 v159, v119, s24, v80
	s_waitcnt vmcnt(22)
	v_lshlrev_b32_e32 v80, 16, v125
	v_and_or_b32 v160, v125, s24, v81
	s_waitcnt vmcnt(20)
	v_lshlrev_b32_e32 v81, 16, v128
	v_lshrrev_b32_e32 v161, 16, v127
	v_and_or_b32 v73, v114, s24, v73
	v_and_or_b32 v78, v115, s22, v78
	v_and_or_b32 v79, v118, s22, v79
	v_and_or_b32 v80, v124, s22, v80
	v_and_or_b32 v81, v127, s22, v81
	v_and_or_b32 v161, v128, s24, v161
	s_waitcnt lgkmcnt(0)
	v_mfma_f32_16x16x32_bf16 v[174:177], v[66:69], v[74:77], 0
	ds_read_b128 v[66:69], v157 offset:37888
	ds_read_b128 v[240:243], v157 offset:41984
	s_waitcnt lgkmcnt(1)
	v_mfma_f32_16x16x32_bf16 v[74:77], v[70:73], v[66:69], v[162:165]
	ds_read_b128 v[66:69], v157 offset:46080
	s_waitcnt lgkmcnt(1)
	v_mfma_f32_16x16x32_bf16 v[162:165], v[70:73], v[240:243], v[166:169]
	ds_read_b128 v[240:243], v157 offset:50176
	s_waitcnt lgkmcnt(1)
	v_mfma_f32_16x16x32_bf16 v[166:169], v[70:73], v[66:69], v[170:173]
	ds_read_b128 v[66:69], v157 offset:38912
	s_waitcnt lgkmcnt(1)
	v_mfma_f32_16x16x32_bf16 v[170:173], v[70:73], v[240:243], v[174:177]
	ds_read_b128 v[240:243], v157 offset:43008
	s_waitcnt lgkmcnt(1)
	v_mfma_f32_16x16x32_bf16 v[70:73], v[78:81], v[66:69], v[74:77]
	ds_read_b128 v[66:69], v157 offset:47104
	s_waitcnt lgkmcnt(1)
	v_mfma_f32_16x16x32_bf16 v[74:77], v[78:81], v[240:243], v[162:165]
	ds_read_b128 v[240:243], v157 offset:51200
	s_waitcnt lgkmcnt(1)
	v_mfma_f32_16x16x32_bf16 v[162:165], v[78:81], v[66:69], v[166:169]
	ds_read_b128 v[66:69], v157 offset:39936
	s_waitcnt lgkmcnt(1)
	v_mfma_f32_16x16x32_bf16 v[166:169], v[78:81], v[240:243], v[170:173]
	ds_read_b128 v[240:243], v157 offset:44032
	s_waitcnt lgkmcnt(1)
	v_mfma_f32_16x16x32_bf16 v[70:73], v[158:161], v[66:69], v[70:73]
	ds_read_b128 v[66:69], v157 offset:48128
	s_waitcnt lgkmcnt(1)
	v_mfma_f32_16x16x32_bf16 v[74:77], v[158:161], v[240:243], v[74:77]
	ds_read_b128 v[240:243], v157 offset:52224
	s_waitcnt lgkmcnt(1)
	v_mfma_f32_16x16x32_bf16 v[78:81], v[158:161], v[66:69], v[162:165]
	s_waitcnt lgkmcnt(0)
	v_mfma_f32_16x16x32_bf16 v[162:165], v[158:161], v[240:243], v[166:169]
	s_nop 15
	s_waitcnt vmcnt(19)
	v_lshrrev_b32_e32 v161, 16, v122
	v_pk_mul_f32 v[66:67], v[70:71], s[0:1] op_sel_hi:[1,0]
	v_pk_mul_f32 v[68:69], v[72:73], s[0:1] op_sel_hi:[1,0]
	v_cvt_pk_bf16_f32 v66, v66, v67
	v_cvt_pk_bf16_f32 v67, v68, v69
	ds_write_b64 v138, v[66:67]
	v_pk_mul_f32 v[66:67], v[74:75], s[0:1] op_sel_hi:[1,0]
	v_pk_mul_f32 v[68:69], v[76:77], s[0:1] op_sel_hi:[1,0]
	v_cvt_pk_bf16_f32 v66, v66, v67
	v_cvt_pk_bf16_f32 v67, v68, v69
	ds_write_b64 v138, v[66:67] offset:8448
	v_pk_mul_f32 v[66:67], v[78:79], s[0:1] op_sel_hi:[1,0]
	v_pk_mul_f32 v[68:69], v[80:81], s[0:1] op_sel_hi:[1,0]
	v_cvt_pk_bf16_f32 v66, v66, v67
	v_cvt_pk_bf16_f32 v67, v68, v69
	ds_write_b64 v138, v[66:67] offset:16896
	v_pk_mul_f32 v[66:67], v[162:163], s[0:1] op_sel_hi:[1,0]
	v_pk_mul_f32 v[68:69], v[164:165], s[0:1] op_sel_hi:[1,0]
	v_cvt_pk_bf16_f32 v66, v66, v67
	v_cvt_pk_bf16_f32 v67, v68, v69
	ds_write_b64 v138, v[66:67] offset:25344
	v_lshrrev_b32_e32 v67, 16, v113
	s_waitcnt vmcnt(14)
	v_lshrrev_b32_e32 v68, 16, v132
	s_waitcnt vmcnt(12)
	v_lshrrev_b32_e32 v69, 16, v134
	v_lshlrev_b32_e32 v66, 16, v131
	v_and_or_b32 v70, v131, s24, v67
	v_lshlrev_b32_e32 v67, 16, v133
	v_and_or_b32 v71, v133, s24, v68
	s_waitcnt vmcnt(11)
	v_lshlrev_b32_e32 v68, 16, v135
	v_and_or_b32 v72, v135, s24, v69
	s_waitcnt vmcnt(9)
	v_lshlrev_b32_e32 v69, 16, v137
	v_and_or_b32 v66, v113, s22, v66
	v_and_or_b32 v67, v132, s22, v67
	v_and_or_b32 v68, v134, s22, v68
	v_and_or_b32 v69, v136, s22, v69
	ds_read_b128 v[74:77], v157 offset:36864
	v_lshrrev_b32_e32 v79, 16, v121
	s_waitcnt lgkmcnt(0)
	v_mfma_f32_16x16x32_bf16 v[162:165], v[66:69], v[74:77], 0
	ds_read_b128 v[74:77], v157 offset:40960
	v_lshrrev_b32_e32 v80, 16, v117
	s_waitcnt lgkmcnt(0)
; #define LASP __attribute__((address_space(3)))
; __device__ __forceinline__ unsigned cvtpk(float lo, float hi) { return pk2(lo, hi); }
; __device__ __forceinline__ f32x4 mfma16(bf16x8 a, bf16x8 b, f32x4 c) { return mfma16_g(a, b, c); }
; #define F2_LOADW(uu_) do { const unsigned* src_ = c.FY + (size_t)((((uu_) >> 6) * 4 + g) * 64 + ((uu_) & 63)) * 4096; \
;         _Pragma("unroll") for (int nn = 0; nn < 2; ++nn) _Pragma("unroll") for (int ks = 0; ks < 2; ++ks) _Pragma("unroll") for (int j = 0; j < 8; ++j) \
;             wq[nn][ks][j] = src_[(32 * ks + 8 * fq + j) * 64 + 16 * (2 * nh + nn) + fr]; } while (0)
; __device__ __forceinline__ void fft2_phase_mfma(const Ctx& c, int l, unsigned char* lds_raw) {
;     ...
;         for (int nn = 0; nn < 2; ++nn) {
;             bf16x8 bre[2], bim[2];
; #pragma unroll
;             for (int ks = 0; ks < 2; ++ks) {
;                 unsigned w[8];
; #pragma unroll
;                 for (int j = 0; j < 8; ++j) w[j] = wq[nn][ks][j];
;                 u32x4 re, im;
; #pragma unroll
;                 for (int e = 0; e < 4; ++e) { re[e] = (w[2 * e] & 0xffffu) | (w[2 * e + 1] << 16); im[e] = (w[2 * e] >> 16) | (w[2 * e + 1] & 0xffff0000u); }
;                 bre[ks] = __builtin_bit_cast(bf16x8, re); bim[ks] = __builtin_bit_cast(bf16x8, im);
;             }
;             f32x4 dacc[4];
; #pragma unroll
;             for (int m = 0; m < 4; ++m) dacc[m] = (f32x4){0.f, 0.f, 0.f, 0.f};
; #pragma unroll
;             for (int ks = 0; ks < 2; ++ks) {
; #pragma unroll
;                 for (int m = 0; m < 4; ++m) dacc[m] = mfma16(bre[ks], FT2(m, ks, 0), dacc[m]);
;                 __builtin_amdgcn_sched_barrier(0);
; #pragma unroll
;                 for (int m = 0; m < 4; ++m) dacc[m] = mfma16(bim[ks], FT2(m, ks, 1), dacc[m]);
;                 __builtin_amdgcn_sched_barrier(0);
;             }
;             asm volatile("s_nop 15" : "+v"(dacc[0]), "+v"(dacc[1]), "+v"(dacc[2]), "+v"(dacc[3]));
; #pragma unroll
;             for (int m = 0; m < 4; ++m) {
;                 u32x2 wv; wv.x = cvtpk(dacc[m][0] * (1.f / 512.f), dacc[m][1] * (1.f / 512.f)); wv.y = cvtpk(dacc[m][2] * (1.f / 512.f), dacc[m][3] * (1.f / 512.f));
;                 *(LASP u32x2*)(F + (16 * m + fr) * 528 + (g * 64 + 16 * (2 * nh + nn) + 4 * fq) * 2) = wv;
;             }
;         }
;         if (un < NB * 64) F2_LOADW(un);
	v_mfma_f32_16x16x32_bf16 v[166:169], v[66:69], v[74:77], 0
	ds_read_b128 v[74:77], v157 offset:45056
	v_lshrrev_b32_e32 v81, 16, v126
	s_waitcnt lgkmcnt(0)
	v_mfma_f32_16x16x32_bf16 v[170:173], v[66:69], v[74:77], 0
	ds_read_b128 v[74:77], v157 offset:49152
	v_lshrrev_b32_e32 v73, 16, v136
	v_lshlrev_b32_e32 v78, 16, v120
	v_and_or_b32 v158, v120, s24, v79
	v_lshlrev_b32_e32 v79, 16, v129
	v_and_or_b32 v159, v129, s24, v80
	v_lshlrev_b32_e32 v80, 16, v123
	v_and_or_b32 v160, v123, s24, v81
	s_waitcnt vmcnt(8)
	v_lshlrev_b32_e32 v81, 16, v130
	v_and_or_b32 v73, v137, s24, v73
	v_and_or_b32 v78, v121, s22, v78
	v_and_or_b32 v79, v117, s22, v79
	v_and_or_b32 v80, v126, s22, v80
	v_and_or_b32 v81, v122, s22, v81
	v_and_or_b32 v161, v130, s24, v161
	s_waitcnt lgkmcnt(0)
	v_mfma_f32_16x16x32_bf16 v[174:177], v[66:69], v[74:77], 0
	ds_read_b128 v[66:69], v157 offset:37888
	ds_read_b128 v[240:243], v157 offset:41984
	s_waitcnt lgkmcnt(1)
	v_mfma_f32_16x16x32_bf16 v[74:77], v[70:73], v[66:69], v[162:165]
	ds_read_b128 v[66:69], v157 offset:46080
	s_waitcnt lgkmcnt(1)
	v_mfma_f32_16x16x32_bf16 v[162:165], v[70:73], v[240:243], v[166:169]
	ds_read_b128 v[240:243], v157 offset:50176
	s_waitcnt lgkmcnt(1)
	v_mfma_f32_16x16x32_bf16 v[166:169], v[70:73], v[66:69], v[170:173]
	ds_read_b128 v[66:69], v157 offset:38912
	s_waitcnt lgkmcnt(1)
	v_mfma_f32_16x16x32_bf16 v[170:173], v[70:73], v[240:243], v[174:177]
	ds_read_b128 v[240:243], v157 offset:43008
	s_waitcnt lgkmcnt(1)
	v_mfma_f32_16x16x32_bf16 v[70:73], v[78:81], v[66:69], v[74:77]
	ds_read_b128 v[66:69], v157 offset:47104
	s_waitcnt lgkmcnt(1)
	v_mfma_f32_16x16x32_bf16 v[74:77], v[78:81], v[240:243], v[162:165]
	ds_read_b128 v[240:243], v157 offset:51200
	s_waitcnt lgkmcnt(1)
	v_mfma_f32_16x16x32_bf16 v[162:165], v[78:81], v[66:69], v[166:169]
	ds_read_b128 v[66:69], v157 offset:39936
	s_waitcnt lgkmcnt(1)
	v_mfma_f32_16x16x32_bf16 v[166:169], v[78:81], v[240:243], v[170:173]
	ds_read_b128 v[240:243], v157 offset:44032
	s_waitcnt lgkmcnt(1)
	v_mfma_f32_16x16x32_bf16 v[70:73], v[158:161], v[66:69], v[70:73]
	ds_read_b128 v[66:69], v157 offset:48128
	s_waitcnt lgkmcnt(1)
	v_mfma_f32_16x16x32_bf16 v[74:77], v[158:161], v[240:243], v[74:77]
	ds_read_b128 v[240:243], v157 offset:52224
	s_waitcnt lgkmcnt(1)
	v_mfma_f32_16x16x32_bf16 v[78:81], v[158:161], v[66:69], v[162:165]
	s_waitcnt lgkmcnt(0)
	v_mfma_f32_16x16x32_bf16 v[162:165], v[158:161], v[240:243], v[166:169]
	s_nop 15
	s_add_i32 s29, s1, s3
	v_pk_mul_f32 v[66:67], v[70:71], s[0:1] op_sel_hi:[1,0]
	v_pk_mul_f32 v[68:69], v[72:73], s[0:1] op_sel_hi:[1,0]
	v_cvt_pk_bf16_f32 v66, v66, v67
	v_cvt_pk_bf16_f32 v67, v68, v69
	ds_write_b64 v138, v[66:67] offset:32
	v_pk_mul_f32 v[66:67], v[74:75], s[0:1] op_sel_hi:[1,0]
	v_pk_mul_f32 v[68:69], v[76:77], s[0:1] op_sel_hi:[1,0]
	v_cvt_pk_bf16_f32 v66, v66, v67
	v_cvt_pk_bf16_f32 v67, v68, v69
	ds_write_b64 v138, v[66:67] offset:8480
	v_pk_mul_f32 v[66:67], v[78:79], s[0:1] op_sel_hi:[1,0]
	v_pk_mul_f32 v[68:69], v[80:81], s[0:1] op_sel_hi:[1,0]
	s_cmpk_lt_i32 s29, 0x200
	v_cvt_pk_bf16_f32 v66, v66, v67
	v_cvt_pk_bf16_f32 v67, v68, v69
	s_cselect_b64 s[20:21], -1, 0
	s_cmpk_gt_i32 s29, 0x1ff
	ds_write_b64 v138, v[66:67] offset:16928
	v_pk_mul_f32 v[66:67], v[162:163], s[0:1] op_sel_hi:[1,0]
	v_pk_mul_f32 v[68:69], v[164:165], s[0:1] op_sel_hi:[1,0]
	s_cselect_b64 s[6:7], -1, 0
	v_cvt_pk_bf16_f32 v66, v66, v67
	v_cvt_pk_bf16_f32 v67, v68, v69
	s_and_b64 vcc, exec, s[6:7]
	ds_write_b64 v138, v[66:67] offset:25376
	s_cbranch_vccnz .LBB0_1170
	s_lshr_b32 s2, s29, 4
	s_and_b32 s2, s2, 0x3fffffc
	s_add_i32 s2, s2, s27
	s_lshl_b32 s2, s2, 6
	s_and_b32 s30, s29, 63
	s_or_b32 s30, s2, s30
	s_ashr_i32 s31, s30, 31
	s_lshl_b64 s[30:31], s[30:31], 14
	s_add_u32 s30, s23, s30
	s_addc_u32 s31, s25, s31
	global_load_dword v99, v139, s[30:31]
	global_load_dword v103, v139, s[30:31] offset:256
	global_load_dword v105, v139, s[30:31] offset:512
	global_load_dword v107, v139, s[30:31] offset:768
	global_load_dword v110, v139, s[30:31] offset:1024
	global_load_dword v111, v139, s[30:31] offset:1280
	global_load_dword v112, v139, s[30:31] offset:1536
	global_load_dword v113, v139, s[30:31] offset:64
	global_load_dword v114, v139, s[30:31] offset:1792
	global_load_dword v115, v140, s[30:31]
	global_load_dword v116, v141, s[30:31]
	global_load_dword v118, v142, s[30:31]
	global_load_dword v119, v143, s[30:31]
	global_load_dword v117, v142, s[30:31] offset:64
	global_load_dword v120, v141, s[30:31] offset:64
	global_load_dword v121, v140, s[30:31] offset:64
	global_load_dword v124, v144, s[30:31]
	global_load_dword v125, v145, s[30:31]
	global_load_dword v127, v146, s[30:31]
	global_load_dword v128, v147, s[30:31]
	global_load_dword v122, v146, s[30:31] offset:64
	global_load_dword v123, v145, s[30:31] offset:64
	global_load_dword v126, v144, s[30:31] offset:64
	global_load_dword v129, v143, s[30:31] offset:64
	global_load_dword v131, v148, s[30:31] offset:64
	global_load_dword v132, v149, s[30:31] offset:64
	global_load_dword v133, v150, s[30:31] offset:64
	global_load_dword v134, v151, s[30:31] offset:64
	global_load_dword v135, v152, s[30:31] offset:64
	global_load_dword v136, v153, s[30:31] offset:64
	global_load_dword v137, v154, s[30:31] offset:64
	global_load_dword v130, v147, s[30:31] offset:64

; __device__ __forceinline__ f32x4 mfma16(bf16x8 a, bf16x8 b, f32x4 c) { return mfma16_g(a, b, c); }
; __device__ __forceinline__ void fft1_phase_wave(const Ctx& c, unsigned char* lds_raw) {
;     ...
;         for (int n = 0; n < 4; ++n) {
;             f32x4 wre[4], wim[4];
; #pragma unroll
;             for (int m = 0; m < 4; ++m) { wre[m] = (f32x4){0.f, 0.f, 0.f, 0.f}; wim[m] = wre[m]; }
; #pragma unroll
;             for (int ks = 0; ks < 2; ++ks) {
;                 const bf16x8 cb = FT_B(ks, n, 0), sb = FT_B(ks, n, 1);
; #pragma unroll
;                 for (int m = 0; m < 4; ++m) { wre[m] = mfma16(ua[m][ks], cb, wre[m]); wim[m] = mfma16(ua[m][ks], sb, wim[m]); }
;                 __builtin_amdgcn_sched_barrier(0);
;             }
;             asm volatile("s_nop 15\n\ts_nop 15" : "+v"(wre[0]), "+v"(wre[1]), "+v"(wre[2]), "+v"(wre[3]), "+v"(wim[0]), "+v"(wim[1]), "+v"(wim[2]), "+v"(wim[3]));
;             bf16x8 bre[2], bim[2];
; #pragma unroll
;             for (int ks = 0; ks < 2; ++ks) { bre[ks] = pack8(wre[2 * ks], wre[2 * ks + 1]); bim[ks] = pack8(wim[2 * ks], wim[2 * ks + 1]); }
;             asm volatile("s_nop 7" : "+v"(bre[0]), "+v"(bre[1]), "+v"(bim[0]), "+v"(bim[1]));
; #pragma unroll
;             for (int mp = 0; mp < 2; ++mp) {
;                 f32x4 yre[2], yin[2];
; #pragma unroll
;                 for (int q = 0; q < 2; ++q) { yre[q] = (f32x4){0.f, 0.f, 0.f, 0.f}; yin[q] = yre[q]; }
; #pragma unroll
;                 for (int ks = 0; ks < 2; ++ks) {
; #pragma unroll
;                     for (int q = 0; q < 2; ++q) { const bf16x8 ca = FT_A(2 * mp + q, ks, 0); yre[q] = mfma16(bre[ks], ca, yre[q]); yin[q] = mfma16(bim[ks], ca, yin[q]); }
;                     __builtin_amdgcn_sched_barrier(0);
; #pragma unroll
;                     for (int q = 0; q < 2; ++q) { yre[q] = mfma16(bim[ks], FT_A(2 * mp + q, ks, 2), yre[q]); yin[q] = mfma16(bre[ks], FT_A(2 * mp + q, ks, 1), yin[q]); }
;                     __builtin_amdgcn_sched_barrier(0);
;                 }
;                 asm volatile("s_nop 15\n\ts_nop 15" : "+v"(yre[0]), "+v"(yin[0]), "+v"(yre[1]), "+v"(yin[1]));
; #pragma unroll
;                 for (int q = 0; q < 2; ++q) {
;                     const int k1 = 16 * (2 * mp + q) + fr;
;                     const float2 tw = twv[mp][q];
;                     u32x4 wv;
; #pragma unroll
.LBB0_2465:
	ds_read_b128 v[78:81], v44
	ds_read_b128 v[82:85], v44 offset:1024
	s_waitcnt lgkmcnt(1)
	v_mfma_f32_16x16x32_bf16 v[86:89], v[2:5], v[78:81], 0
	s_waitcnt lgkmcnt(0)
	v_mfma_f32_16x16x32_bf16 v[90:93], v[2:5], v[82:85], 0
	v_mfma_f32_16x16x32_bf16 v[94:97], v[10:13], v[78:81], 0
	v_mfma_f32_16x16x32_bf16 v[98:101], v[10:13], v[82:85], 0
	v_mfma_f32_16x16x32_bf16 v[102:105], v[18:21], v[78:81], 0
	v_mfma_f32_16x16x32_bf16 v[106:109], v[18:21], v[82:85], 0
	v_mfma_f32_16x16x32_bf16 v[110:113], v[26:29], v[78:81], 0
	v_mfma_f32_16x16x32_bf16 v[78:81], v[26:29], v[82:85], 0
	ds_read_b128 v[82:85], v44 offset:8192
	ds_read_b128 v[114:117], v44 offset:9216
	s_waitcnt lgkmcnt(1)
	v_mfma_f32_16x16x32_bf16 v[86:89], v[6:9], v[82:85], v[86:89]
	s_waitcnt lgkmcnt(0)
	v_mfma_f32_16x16x32_bf16 v[90:93], v[6:9], v[114:117], v[90:93]
	v_mfma_f32_16x16x32_bf16 v[94:97], v[14:17], v[82:85], v[94:97]
	v_mfma_f32_16x16x32_bf16 v[98:101], v[14:17], v[114:117], v[98:101]
	v_mfma_f32_16x16x32_bf16 v[102:105], v[22:25], v[82:85], v[102:105]
	v_mfma_f32_16x16x32_bf16 v[106:109], v[22:25], v[114:117], v[106:109]
	v_mfma_f32_16x16x32_bf16 v[110:113], v[30:33], v[82:85], v[110:113]
	v_mfma_f32_16x16x32_bf16 v[78:81], v[30:33], v[114:117], v[78:81]
	s_nop 15
	s_nop 15
	s_nop 0
	v_cvt_pk_bf16_f32 v82, v86, v87
	v_cvt_pk_bf16_f32 v83, v88, v89
	v_cvt_pk_bf16_f32 v84, v94, v95
	v_cvt_pk_bf16_f32 v85, v96, v97
	v_cvt_pk_bf16_f32 v86, v90, v91
	v_cvt_pk_bf16_f32 v87, v92, v93
	v_cvt_pk_bf16_f32 v88, v98, v99
	v_cvt_pk_bf16_f32 v89, v100, v101
	v_cvt_pk_bf16_f32 v90, v102, v103
	v_cvt_pk_bf16_f32 v91, v104, v105
	v_cvt_pk_bf16_f32 v92, v110, v111
	v_cvt_pk_bf16_f32 v93, v112, v113
	v_cvt_pk_bf16_f32 v94, v106, v107
	v_cvt_pk_bf16_f32 v95, v108, v109
	v_cvt_pk_bf16_f32 v96, v78, v79
	v_cvt_pk_bf16_f32 v97, v80, v81
	s_nop 7
	ds_read_b128 v[78:81], v72 offset:16384
	ds_read_b128 v[240:243], v72 offset:22528
	s_waitcnt lgkmcnt(1)
	v_mfma_f32_16x16x32_bf16 v[98:101], v[82:85], v[78:81], 0
	v_mfma_f32_16x16x32_bf16 v[102:105], v[86:89], v[78:81], 0
	ds_read_b128 v[78:81], v72 offset:18432
	s_waitcnt lgkmcnt(1)
	v_mfma_f32_16x16x32_bf16 v[106:109], v[82:85], v[240:243], 0
	v_mfma_f32_16x16x32_bf16 v[110:113], v[86:89], v[240:243], 0
	ds_read_b128 v[240:243], v72 offset:17408
	s_waitcnt lgkmcnt(1)
	v_mfma_f32_16x16x32_bf16 v[98:101], v[86:89], v[78:81], v[98:101]
	ds_read_b128 v[78:81], v72 offset:24576
	s_waitcnt lgkmcnt(1)
	v_mfma_f32_16x16x32_bf16 v[102:105], v[82:85], v[240:243], v[102:105]
	ds_read_b128 v[240:243], v72 offset:23552
	s_waitcnt lgkmcnt(1)
	v_mfma_f32_16x16x32_bf16 v[106:109], v[86:89], v[78:81], v[106:109]
	ds_read_b128 v[78:81], v72 offset:19456
	s_waitcnt lgkmcnt(1)
	v_mfma_f32_16x16x32_bf16 v[110:113], v[82:85], v[240:243], v[110:113]
	ds_read_b128 v[240:243], v72 offset:25600
	s_waitcnt lgkmcnt(1)
	v_mfma_f32_16x16x32_bf16 v[98:101], v[90:93], v[78:81], v[98:101]
	v_mfma_f32_16x16x32_bf16 v[102:105], v[94:97], v[78:81], v[102:105]
	ds_read_b128 v[78:81], v72 offset:21504
	s_waitcnt lgkmcnt(1)
	v_mfma_f32_16x16x32_bf16 v[106:109], v[90:93], v[240:243], v[106:109]
	v_mfma_f32_16x16x32_bf16 v[110:113], v[94:97], v[240:243], v[110:113]
	ds_read_b128 v[240:243], v72 offset:20480
	s_waitcnt lgkmcnt(1)
	v_mfma_f32_16x16x32_bf16 v[98:101], v[94:97], v[78:81], v[98:101]
	ds_read_b128 v[78:81], v72 offset:27648
	s_waitcnt lgkmcnt(1)
	v_mfma_f32_16x16x32_bf16 v[102:105], v[90:93], v[240:243], v[102:105]
	ds_read_b128 v[240:243], v72 offset:26624
	s_waitcnt lgkmcnt(1)
	v_mfma_f32_16x16x32_bf16 v[106:109], v[94:97], v[78:81], v[106:109]
	s_waitcnt lgkmcnt(0)
	v_mfma_f32_16x16x32_bf16 v[110:113], v[90:93], v[240:243], v[110:113]
	s_nop 15
	s_nop 15
	s_nop 1
	v_mov_b32_e32 v80, v102
	v_mov_b32_e32 v81, v98
	v_xor_b32_e32 v79, 0x80000000, v102
	v_mov_b32_e32 v78, v98
	v_pk_mul_f32 v[80:81], v[64:65], v[80:81]
	v_mov_b32_e32 v98, v103
	v_pk_fma_f32 v[78:79], v[56:57], v[78:79], v[80:81] neg_lo:[0,0,1] neg_hi:[0,0,1]
	v_xor_b32_e32 v81, 0x80000000, v103
	v_mov_b32_e32 v80, v99
	v_pk_mul_f32 v[98:99], v[64:65], v[98:99]
	v_cvt_pk_bf16_f32 v78, v78, v79
	v_pk_fma_f32 v[80:81], v[56:57], v[80:81], v[98:99] neg_lo:[0,0,1] neg_hi:[0,0,1]
	v_mov_b32_e32 v98, v104
	v_mov_b32_e32 v99, v100
	v_cvt_pk_bf16_f32 v79, v80, v81
	v_xor_b32_e32 v81, 0x80000000, v104
	v_mov_b32_e32 v80, v100
	v_pk_mul_f32 v[98:99], v[64:65], v[98:99]
	v_mov_b32_e32 v100, v105
	v_pk_fma_f32 v[80:81], v[56:57], v[80:81], v[98:99] neg_lo:[0,0,1] neg_hi:[0,0,1]
	v_xor_b32_e32 v99, 0x80000000, v105
	v_mov_b32_e32 v98, v101
	v_pk_mul_f32 v[100:101], v[64:65], v[100:101]
	v_cvt_pk_bf16_f32 v80, v80, v81
	v_pk_fma_f32 v[98:99], v[56:57], v[98:99], v[100:101] neg_lo:[0,0,1] neg_hi:[0,0,1]
	v_xor_b32_e32 v103, 0x80000000, v113
	v_cvt_pk_bf16_f32 v81, v98, v99
	v_lshl_add_u64 v[98:99], v[54:55], 0, s[4:5]
	global_store_dwordx4 v[98:99], v[78:81], off
	v_mov_b32_e32 v102, v109
	s_nop 0
	v_mov_b32_e32 v80, v110
	v_mov_b32_e32 v81, v106
	v_xor_b32_e32 v79, 0x80000000, v110
	v_mov_b32_e32 v78, v106
	v_pk_mul_f32 v[80:81], v[66:67], v[80:81]
	v_mov_b32_e32 v106, v111
	v_pk_fma_f32 v[78:79], v[58:59], v[78:79], v[80:81] neg_lo:[0,0,1] neg_hi:[0,0,1]
	v_xor_b32_e32 v81, 0x80000000, v111
	v_mov_b32_e32 v80, v107
	v_pk_mul_f32 v[98:99], v[66:67], v[106:107]
	v_cvt_pk_bf16_f32 v78, v78, v79
	v_pk_fma_f32 v[80:81], v[58:59], v[80:81], v[98:99] neg_lo:[0,0,1] neg_hi:[0,0,1]
	v_mov_b32_e32 v98, v112
	v_mov_b32_e32 v99, v108
	v_cvt_pk_bf16_f32 v79, v80, v81
	v_xor_b32_e32 v81, 0x80000000, v112
	v_mov_b32_e32 v80, v108
	v_pk_mul_f32 v[98:99], v[66:67], v[98:99]
	v_mov_b32_e32 v108, v113
	v_pk_fma_f32 v[80:81], v[58:59], v[80:81], v[98:99] neg_lo:[0,0,1] neg_hi:[0,0,1]
	ds_read_b128 v[98:101], v72 offset:28672
	v_pk_mul_f32 v[104:105], v[66:67], v[108:109]
	v_cvt_pk_bf16_f32 v80, v80, v81
	v_pk_fma_f32 v[102:103], v[58:59], v[102:103], v[104:105] neg_lo:[0,0,1] neg_hi:[0,0,1]
	v_lshl_add_u64 v[106:107], v[52:53], 0, s[4:5]
	v_cvt_pk_bf16_f32 v81, v102, v103
	s_waitcnt lgkmcnt(0)
; __device__ __forceinline__ unsigned pk2(float lo, float hi) { const f32x2n v = {lo, hi}; return __builtin_bit_cast(unsigned, __builtin_convertvector(v, bf16x2n)); }
; __device__ __forceinline__ f32x4 mfma16(bf16x8 a, bf16x8 b, f32x4 c) { return mfma16_g(a, b, c); }
; __device__ __forceinline__ void fft1_phase_wave(const Ctx& c, unsigned char* lds_raw) {
;     ...
;             for (int mp = 0; mp < 2; ++mp) {
;                 f32x4 yre[2], yin[2];
; #pragma unroll
;                 for (int q = 0; q < 2; ++q) { yre[q] = (f32x4){0.f, 0.f, 0.f, 0.f}; yin[q] = yre[q]; }
; #pragma unroll
;                 for (int ks = 0; ks < 2; ++ks) {
; #pragma unroll
;                     for (int q = 0; q < 2; ++q) { const bf16x8 ca = FT_A(2 * mp + q, ks, 0); yre[q] = mfma16(bre[ks], ca, yre[q]); yin[q] = mfma16(bim[ks], ca, yin[q]); }
;                     __builtin_amdgcn_sched_barrier(0);
; #pragma unroll
;                     for (int q = 0; q < 2; ++q) { yre[q] = mfma16(bim[ks], FT_A(2 * mp + q, ks, 2), yre[q]); yin[q] = mfma16(bre[ks], FT_A(2 * mp + q, ks, 1), yin[q]); }
;                     __builtin_amdgcn_sched_barrier(0);
;                 }
;                 asm volatile("s_nop 15\n\ts_nop 15" : "+v"(yre[0]), "+v"(yin[0]), "+v"(yre[1]), "+v"(yin[1]));
; #pragma unroll
;                 for (int q = 0; q < 2; ++q) {
;                     const int k1 = 16 * (2 * mp + q) + fr;
;                     const float2 tw = twv[mp][q];
;                     u32x4 wv;
; #pragma unroll
;                     for (int rg = 0; rg < 4; ++rg) { const float yr = yre[q][rg], yi = -yin[q][rg]; wv[rg] = pk2(yr * tw.x + yi * tw.y, yi * tw.x - yr * tw.y); }
;                     *(u32x4*)(c.FY + ((size_t)(bg * 64 + k1) * 64 + s2) * 64 + 16 * n + 4 * fq) = wv;
;                 }
;             }
;         }
;     }
	v_mfma_f32_16x16x32_bf16 v[102:105], v[82:85], v[98:101], 0
	global_store_dwordx4 v[106:107], v[78:81], off
	s_nop 1
	v_mfma_f32_16x16x32_bf16 v[78:81], v[86:89], v[98:101], 0
	ds_read_b128 v[98:101], v72 offset:34816
	ds_read_b128 v[240:243], v72 offset:30720
	s_waitcnt lgkmcnt(1)
	v_mfma_f32_16x16x32_bf16 v[106:109], v[82:85], v[98:101], 0
	v_mfma_f32_16x16x32_bf16 v[110:113], v[86:89], v[98:101], 0
	ds_read_b128 v[98:101], v72 offset:29696
	s_waitcnt lgkmcnt(1)
	v_mfma_f32_16x16x32_bf16 v[102:105], v[86:89], v[240:243], v[102:105]
	ds_read_b128 v[240:243], v72 offset:36864
	s_waitcnt lgkmcnt(1)
	v_mfma_f32_16x16x32_bf16 v[78:81], v[82:85], v[98:101], v[78:81]
	s_waitcnt lgkmcnt(0)
	v_mfma_f32_16x16x32_bf16 v[106:109], v[86:89], v[240:243], v[106:109]
	ds_read_b128 v[86:89], v72 offset:35840
	s_waitcnt lgkmcnt(0)
	v_mfma_f32_16x16x32_bf16 v[98:101], v[82:85], v[86:89], v[110:113]
	ds_read_b128 v[82:85], v72 offset:31744
	ds_read_b128 v[240:243], v72 offset:37888
	s_waitcnt lgkmcnt(1)
	v_mfma_f32_16x16x32_bf16 v[86:89], v[90:93], v[82:85], v[102:105]
	v_mfma_f32_16x16x32_bf16 v[78:81], v[94:97], v[82:85], v[78:81]
	ds_read_b128 v[82:85], v72 offset:33792
	s_waitcnt lgkmcnt(1)
	v_mfma_f32_16x16x32_bf16 v[102:105], v[90:93], v[240:243], v[106:109]
	v_mfma_f32_16x16x32_bf16 v[98:101], v[94:97], v[240:243], v[98:101]
	ds_read_b128 v[240:243], v72 offset:32768
	s_waitcnt lgkmcnt(1)
	v_mfma_f32_16x16x32_bf16 v[86:89], v[94:97], v[82:85], v[86:89]
	ds_read_b128 v[82:85], v72 offset:39936
	s_waitcnt lgkmcnt(1)
	v_mfma_f32_16x16x32_bf16 v[78:81], v[90:93], v[240:243], v[78:81]
	ds_read_b128 v[240:243], v72 offset:38912
	s_waitcnt lgkmcnt(1)
	v_mfma_f32_16x16x32_bf16 v[102:105], v[94:97], v[82:85], v[102:105]
	s_waitcnt lgkmcnt(0)
	v_mfma_f32_16x16x32_bf16 v[94:97], v[90:93], v[240:243], v[98:101]
	s_nop 15
	s_nop 15
	v_lshl_add_u64 v[90:91], v[50:51], 0, s[4:5]
	s_nop 0
	v_xor_b32_e32 v83, 0x80000000, v78
	v_mov_b32_e32 v82, v86
	v_mov_b32_e32 v84, v78
	v_mov_b32_e32 v85, v86
	v_mov_b32_e32 v86, v79
	v_mov_b32_e32 v78, v88
	v_mov_b32_e32 v100, v80
	v_mov_b32_e32 v101, v88
	v_mov_b32_e32 v88, v81
	v_lshl_add_u64 v[92:93], v[48:49], 0, s[4:5]
	s_add_u32 s4, s4, 64
	v_xor_b32_e32 v99, 0x80000000, v79
	v_mov_b32_e32 v98, v87
	v_xor_b32_e32 v79, 0x80000000, v80
	v_xor_b32_e32 v107, 0x80000000, v81
	v_mov_b32_e32 v106, v89
	v_xor_b32_e32 v81, 0x80000000, v94
	v_mov_b32_e32 v80, v102
	v_mov_b32_e32 v108, v94
	v_mov_b32_e32 v109, v102
	v_xor_b32_e32 v111, 0x80000000, v95
	v_mov_b32_e32 v102, v95
	v_xor_b32_e32 v95, 0x80000000, v96
	v_mov_b32_e32 v94, v104
	v_mov_b32_e32 v112, v96
	v_mov_b32_e32 v113, v104
	v_xor_b32_e32 v115, 0x80000000, v97
	v_mov_b32_e32 v104, v97
	v_pk_mul_f32 v[84:85], v[68:69], v[84:85]
	v_pk_mul_f32 v[86:87], v[68:69], v[86:87]
	v_pk_mul_f32 v[96:97], v[68:69], v[100:101]
	v_pk_mul_f32 v[88:89], v[68:69], v[88:89]
	v_mov_b32_e32 v110, v103
	v_mov_b32_e32 v114, v105
	s_addc_u32 s5, s5, 0
	v_pk_mul_f32 v[100:101], v[70:71], v[108:109]
	v_pk_mul_f32 v[102:103], v[70:71], v[102:103]
	v_pk_mul_f32 v[108:109], v[70:71], v[112:113]
	v_pk_mul_f32 v[104:105], v[70:71], v[104:105]
	v_pk_fma_f32 v[82:83], v[60:61], v[82:83], v[84:85] neg_lo:[0,0,1] neg_hi:[0,0,1]
	v_pk_fma_f32 v[84:85], v[60:61], v[98:99], v[86:87] neg_lo:[0,0,1] neg_hi:[0,0,1]
	v_pk_fma_f32 v[86:87], v[60:61], v[78:79], v[96:97] neg_lo:[0,0,1] neg_hi:[0,0,1]
	v_pk_fma_f32 v[88:89], v[60:61], v[106:107], v[88:89] neg_lo:[0,0,1] neg_hi:[0,0,1]
	v_add_u32_e32 v44, 0x800, v44
	s_cmpk_eq_i32 s4, 0x100
	v_pk_fma_f32 v[96:97], v[62:63], v[80:81], v[100:101] neg_lo:[0,0,1] neg_hi:[0,0,1]
	v_pk_fma_f32 v[98:99], v[62:63], v[110:111], v[102:103] neg_lo:[0,0,1] neg_hi:[0,0,1]
	v_pk_fma_f32 v[94:95], v[62:63], v[94:95], v[108:109] neg_lo:[0,0,1] neg_hi:[0,0,1]
	v_pk_fma_f32 v[100:101], v[62:63], v[114:115], v[104:105] neg_lo:[0,0,1] neg_hi:[0,0,1]
	v_cvt_pk_bf16_f32 v78, v82, v83
	v_cvt_pk_bf16_f32 v79, v84, v85
	v_cvt_pk_bf16_f32 v80, v86, v87
	v_cvt_pk_bf16_f32 v81, v88, v89
	v_cvt_pk_bf16_f32 v82, v96, v97
	v_cvt_pk_bf16_f32 v83, v98, v99
	v_cvt_pk_bf16_f32 v84, v94, v95
	v_cvt_pk_bf16_f32 v85, v100, v101
	global_store_dwordx4 v[90:91], v[78:81], off
	global_store_dwordx4 v[92:93], v[82:85], off
	s_cbranch_scc0 .LBB0_2465
	s_add_i32 s2, s2, s3
	s_add_i32 s6, s6, s3
	s_cmpk_gt_i32 s2, 0x7ff
	s_cbranch_scc0 .LBB0_2462

; #define LASP __attribute__((address_space(3)))
; __device__ __forceinline__ unsigned cvtpk(float lo, float hi) { return pk2(lo, hi); }
; __device__ __forceinline__ f32x4 mfma16(bf16x8 a, bf16x8 b, f32x4 c) { return mfma16_g(a, b, c); }
; __device__ __forceinline__ void fft2_phase_mfma(const Ctx& c, int l, unsigned char* lds_raw) {
;     ...
;         for (int nn = 0; nn < 2; ++nn) {
;             bf16x8 bre[2], bim[2];
; #pragma unroll
;             for (int ks = 0; ks < 2; ++ks) {
;                 unsigned w[8];
; #pragma unroll
;                 for (int j = 0; j < 8; ++j) w[j] = wq[nn][ks][j];
;                 u32x4 re, im;
; #pragma unroll
;                 for (int e = 0; e < 4; ++e) { re[e] = (w[2 * e] & 0xffffu) | (w[2 * e + 1] << 16); im[e] = (w[2 * e] >> 16) | (w[2 * e + 1] & 0xffff0000u); }
;                 bre[ks] = __builtin_bit_cast(bf16x8, re); bim[ks] = __builtin_bit_cast(bf16x8, im);
;             }
;             f32x4 dacc[4];
; #pragma unroll
;             for (int m = 0; m < 4; ++m) dacc[m] = (f32x4){0.f, 0.f, 0.f, 0.f};
; #pragma unroll
;             for (int ks = 0; ks < 2; ++ks) {
; #pragma unroll
;                 for (int m = 0; m < 4; ++m) dacc[m] = mfma16(bre[ks], FT2(m, ks, 0), dacc[m]);
;                 __builtin_amdgcn_sched_barrier(0);
; #pragma unroll
;                 for (int m = 0; m < 4; ++m) dacc[m] = mfma16(bim[ks], FT2(m, ks, 1), dacc[m]);
;                 __builtin_amdgcn_sched_barrier(0);
;             }
;             asm volatile("s_nop 15" : "+v"(dacc[0]), "+v"(dacc[1]), "+v"(dacc[2]), "+v"(dacc[3]));
; #pragma unroll
;             for (int m = 0; m < 4; ++m) {
;                 u32x2 wv; wv.x = cvtpk(dacc[m][0] * (1.f / 512.f), dacc[m][1] * (1.f / 512.f)); wv.y = cvtpk(dacc[m][2] * (1.f / 512.f), dacc[m][3] * (1.f / 512.f));
;                 *(LASP u32x2*)(F + (16 * m + fr) * 528 + (g * 64 + 16 * (2 * nh + nn) + 4 * fq) * 2) = wv;
;             }
.LBB0_2528:
	s_waitcnt vmcnt(39)
	v_lshrrev_b32_e32 v67, 16, v101
	s_waitcnt vmcnt(37)
	v_lshrrev_b32_e32 v68, 16, v107
	s_waitcnt vmcnt(35)
	v_lshrrev_b32_e32 v69, 16, v112
	v_lshlrev_b32_e32 v66, 16, v105
	v_and_or_b32 v70, v105, s22, v67
	v_lshlrev_b32_e32 v67, 16, v109
	v_and_or_b32 v71, v109, s22, v68
	s_waitcnt vmcnt(34)
	v_lshlrev_b32_e32 v68, 16, v113
	v_and_or_b32 v72, v113, s22, v69
	s_waitcnt vmcnt(31)
	v_lshlrev_b32_e32 v69, 16, v116
	v_add_u32_e32 v159, 0, v1
	v_and_or_b32 v66, v101, s20, v66
	v_and_or_b32 v67, v107, s20, v67
	v_and_or_b32 v68, v112, s20, v68
	v_and_or_b32 v69, v114, s20, v69
	ds_read_b128 v[74:77], v159 offset:36864
	s_waitcnt vmcnt(30)
	v_lshrrev_b32_e32 v79, 16, v117
	s_waitcnt lgkmcnt(0)
	v_mfma_f32_16x16x32_bf16 v[164:167], v[66:69], v[74:77], 0
	ds_read_b128 v[74:77], v159 offset:40960
	s_waitcnt vmcnt(28)
	v_lshrrev_b32_e32 v80, 16, v120
	s_waitcnt lgkmcnt(0)
	v_mfma_f32_16x16x32_bf16 v[168:171], v[66:69], v[74:77], 0
	ds_read_b128 v[74:77], v159 offset:45056
	s_waitcnt vmcnt(23)
	v_lshrrev_b32_e32 v81, 16, v126
	s_waitcnt lgkmcnt(0)
	v_mfma_f32_16x16x32_bf16 v[172:175], v[66:69], v[74:77], 0
	ds_read_b128 v[74:77], v159 offset:49152
	v_lshrrev_b32_e32 v73, 16, v114
	v_lshlrev_b32_e32 v78, 16, v118
	v_and_or_b32 v160, v118, s22, v79
	v_lshlrev_b32_e32 v79, 16, v121
	v_and_or_b32 v161, v121, s22, v80
	s_waitcnt vmcnt(22)
	v_lshlrev_b32_e32 v80, 16, v127
	v_and_or_b32 v162, v127, s22, v81
	s_waitcnt vmcnt(20)
	v_lshlrev_b32_e32 v81, 16, v130
	v_lshrrev_b32_e32 v163, 16, v129
	v_and_or_b32 v73, v116, s22, v73
	v_and_or_b32 v78, v117, s20, v78
	v_and_or_b32 v79, v120, s20, v79
	v_and_or_b32 v80, v126, s20, v80
	v_and_or_b32 v81, v129, s20, v81
	v_and_or_b32 v163, v130, s22, v163
	s_waitcnt lgkmcnt(0)
	v_mfma_f32_16x16x32_bf16 v[176:179], v[66:69], v[74:77], 0
	ds_read_b128 v[66:69], v159 offset:37888
	ds_read_b128 v[240:243], v159 offset:41984
	s_waitcnt lgkmcnt(1)
	v_mfma_f32_16x16x32_bf16 v[74:77], v[70:73], v[66:69], v[164:167]
	ds_read_b128 v[66:69], v159 offset:46080
	s_waitcnt lgkmcnt(1)
	v_mfma_f32_16x16x32_bf16 v[164:167], v[70:73], v[240:243], v[168:171]
	ds_read_b128 v[240:243], v159 offset:50176
	s_waitcnt lgkmcnt(1)
	v_mfma_f32_16x16x32_bf16 v[168:171], v[70:73], v[66:69], v[172:175]
	ds_read_b128 v[66:69], v159 offset:38912
	s_waitcnt lgkmcnt(1)
	v_mfma_f32_16x16x32_bf16 v[172:175], v[70:73], v[240:243], v[176:179]
	ds_read_b128 v[240:243], v159 offset:43008
	s_waitcnt lgkmcnt(1)
	v_mfma_f32_16x16x32_bf16 v[70:73], v[78:81], v[66:69], v[74:77]
	ds_read_b128 v[66:69], v159 offset:47104
	s_waitcnt lgkmcnt(1)
	v_mfma_f32_16x16x32_bf16 v[74:77], v[78:81], v[240:243], v[164:167]
	ds_read_b128 v[240:243], v159 offset:51200
	s_waitcnt lgkmcnt(1)
	v_mfma_f32_16x16x32_bf16 v[164:167], v[78:81], v[66:69], v[168:171]
	ds_read_b128 v[66:69], v159 offset:39936
	s_waitcnt lgkmcnt(1)
	v_mfma_f32_16x16x32_bf16 v[168:171], v[78:81], v[240:243], v[172:175]
	ds_read_b128 v[240:243], v159 offset:44032
	s_waitcnt lgkmcnt(1)
	v_mfma_f32_16x16x32_bf16 v[70:73], v[160:163], v[66:69], v[70:73]
	ds_read_b128 v[66:69], v159 offset:48128
	s_waitcnt lgkmcnt(1)
	v_mfma_f32_16x16x32_bf16 v[74:77], v[160:163], v[240:243], v[74:77]
	ds_read_b128 v[240:243], v159 offset:52224
	s_waitcnt lgkmcnt(1)
	v_mfma_f32_16x16x32_bf16 v[78:81], v[160:163], v[66:69], v[164:167]
	s_waitcnt lgkmcnt(0)
	v_mfma_f32_16x16x32_bf16 v[164:167], v[160:163], v[240:243], v[168:171]
	s_nop 15
	s_waitcnt vmcnt(19)
	v_lshrrev_b32_e32 v163, 16, v124
	v_pk_mul_f32 v[66:67], v[70:71], s[0:1] op_sel_hi:[1,0]
	v_pk_mul_f32 v[68:69], v[72:73], s[0:1] op_sel_hi:[1,0]
	v_cvt_pk_bf16_f32 v66, v66, v67
	v_cvt_pk_bf16_f32 v67, v68, v69
	ds_write_b64 v140, v[66:67]
	v_pk_mul_f32 v[66:67], v[74:75], s[0:1] op_sel_hi:[1,0]
	v_pk_mul_f32 v[68:69], v[76:77], s[0:1] op_sel_hi:[1,0]
	v_cvt_pk_bf16_f32 v66, v66, v67
	v_cvt_pk_bf16_f32 v67, v68, v69
	ds_write_b64 v140, v[66:67] offset:8448
	v_pk_mul_f32 v[66:67], v[78:79], s[0:1] op_sel_hi:[1,0]
	v_pk_mul_f32 v[68:69], v[80:81], s[0:1] op_sel_hi:[1,0]
	v_cvt_pk_bf16_f32 v66, v66, v67
	v_cvt_pk_bf16_f32 v67, v68, v69
	ds_write_b64 v140, v[66:67] offset:16896
	v_pk_mul_f32 v[66:67], v[164:165], s[0:1] op_sel_hi:[1,0]
	v_pk_mul_f32 v[68:69], v[166:167], s[0:1] op_sel_hi:[1,0]
	v_cvt_pk_bf16_f32 v66, v66, v67
	v_cvt_pk_bf16_f32 v67, v68, v69
	ds_write_b64 v140, v[66:67] offset:25344
	v_lshrrev_b32_e32 v67, 16, v115
	s_waitcnt vmcnt(14)
	v_lshrrev_b32_e32 v68, 16, v134
	s_waitcnt vmcnt(12)
	v_lshrrev_b32_e32 v69, 16, v136
	v_lshlrev_b32_e32 v66, 16, v133
	v_and_or_b32 v70, v133, s22, v67
	v_lshlrev_b32_e32 v67, 16, v135
	v_and_or_b32 v71, v135, s22, v68
	s_waitcnt vmcnt(11)
	v_lshlrev_b32_e32 v68, 16, v137
	v_and_or_b32 v72, v137, s22, v69
	s_waitcnt vmcnt(9)
	v_lshlrev_b32_e32 v69, 16, v139
	v_and_or_b32 v66, v115, s20, v66
	v_and_or_b32 v67, v134, s20, v67
	v_and_or_b32 v68, v136, s20, v68
	v_and_or_b32 v69, v138, s20, v69
	ds_read_b128 v[74:77], v159 offset:36864
	v_lshrrev_b32_e32 v79, 16, v123
	s_waitcnt lgkmcnt(0)
	v_mfma_f32_16x16x32_bf16 v[164:167], v[66:69], v[74:77], 0
	ds_read_b128 v[74:77], v159 offset:40960
	v_lshrrev_b32_e32 v80, 16, v119
	s_waitcnt lgkmcnt(0)
; #define LASP __attribute__((address_space(3)))
; __device__ __forceinline__ unsigned cvtpk(float lo, float hi) { return pk2(lo, hi); }
; __device__ __forceinline__ f32x4 mfma16(bf16x8 a, bf16x8 b, f32x4 c) { return mfma16_g(a, b, c); }
; #define F2_LOADW(uu_) do { const unsigned* src_ = c.FY + (size_t)((((uu_) >> 6) * 4 + g) * 64 + ((uu_) & 63)) * 4096; \
;         _Pragma("unroll") for (int nn = 0; nn < 2; ++nn) _Pragma("unroll") for (int ks = 0; ks < 2; ++ks) _Pragma("unroll") for (int j = 0; j < 8; ++j) \
;             wq[nn][ks][j] = src_[(32 * ks + 8 * fq + j) * 64 + 16 * (2 * nh + nn) + fr]; } while (0)
; __device__ __forceinline__ void fft2_phase_mfma(const Ctx& c, int l, unsigned char* lds_raw) {
;     ...
;         for (int nn = 0; nn < 2; ++nn) {
;             bf16x8 bre[2], bim[2];
; #pragma unroll
;             for (int ks = 0; ks < 2; ++ks) {
;                 unsigned w[8];
; #pragma unroll
;                 for (int j = 0; j < 8; ++j) w[j] = wq[nn][ks][j];
;                 u32x4 re, im;
; #pragma unroll
;                 for (int e = 0; e < 4; ++e) { re[e] = (w[2 * e] & 0xffffu) | (w[2 * e + 1] << 16); im[e] = (w[2 * e] >> 16) | (w[2 * e + 1] & 0xffff0000u); }
;                 bre[ks] = __builtin_bit_cast(bf16x8, re); bim[ks] = __builtin_bit_cast(bf16x8, im);
;             }
;             f32x4 dacc[4];
; #pragma unroll
;             for (int m = 0; m < 4; ++m) dacc[m] = (f32x4){0.f, 0.f, 0.f, 0.f};
; #pragma unroll
;             for (int ks = 0; ks < 2; ++ks) {
; #pragma unroll
;                 for (int m = 0; m < 4; ++m) dacc[m] = mfma16(bre[ks], FT2(m, ks, 0), dacc[m]);
;                 __builtin_amdgcn_sched_barrier(0);
; #pragma unroll
;                 for (int m = 0; m < 4; ++m) dacc[m] = mfma16(bim[ks], FT2(m, ks, 1), dacc[m]);
;                 __builtin_amdgcn_sched_barrier(0);
;             }
;             asm volatile("s_nop 15" : "+v"(dacc[0]), "+v"(dacc[1]), "+v"(dacc[2]), "+v"(dacc[3]));
; #pragma unroll
;             for (int m = 0; m < 4; ++m) {
;                 u32x2 wv; wv.x = cvtpk(dacc[m][0] * (1.f / 512.f), dacc[m][1] * (1.f / 512.f)); wv.y = cvtpk(dacc[m][2] * (1.f / 512.f), dacc[m][3] * (1.f / 512.f));
;                 *(LASP u32x2*)(F + (16 * m + fr) * 528 + (g * 64 + 16 * (2 * nh + nn) + 4 * fq) * 2) = wv;
;             }
;         }
;         if (un < NB * 64) F2_LOADW(un);
	v_mfma_f32_16x16x32_bf16 v[168:171], v[66:69], v[74:77], 0
	ds_read_b128 v[74:77], v159 offset:45056
	v_lshrrev_b32_e32 v81, 16, v128
	s_waitcnt lgkmcnt(0)
	v_mfma_f32_16x16x32_bf16 v[172:175], v[66:69], v[74:77], 0
	ds_read_b128 v[74:77], v159 offset:49152
	v_lshrrev_b32_e32 v73, 16, v138
	v_lshlrev_b32_e32 v78, 16, v122
	v_and_or_b32 v160, v122, s22, v79
	v_lshlrev_b32_e32 v79, 16, v131
	v_and_or_b32 v161, v131, s22, v80
	v_lshlrev_b32_e32 v80, 16, v125
	v_and_or_b32 v162, v125, s22, v81
	s_waitcnt vmcnt(8)
	v_lshlrev_b32_e32 v81, 16, v132
	v_and_or_b32 v73, v139, s22, v73
	v_and_or_b32 v78, v123, s20, v78
	v_and_or_b32 v79, v119, s20, v79
	v_and_or_b32 v80, v128, s20, v80
	v_and_or_b32 v81, v124, s20, v81
	v_and_or_b32 v163, v132, s22, v163
	s_waitcnt lgkmcnt(0)
	v_mfma_f32_16x16x32_bf16 v[176:179], v[66:69], v[74:77], 0
	ds_read_b128 v[66:69], v159 offset:37888
	ds_read_b128 v[240:243], v159 offset:41984
	s_waitcnt lgkmcnt(1)
	v_mfma_f32_16x16x32_bf16 v[74:77], v[70:73], v[66:69], v[164:167]
	ds_read_b128 v[66:69], v159 offset:46080
	s_waitcnt lgkmcnt(1)
	v_mfma_f32_16x16x32_bf16 v[164:167], v[70:73], v[240:243], v[168:171]
	ds_read_b128 v[240:243], v159 offset:50176
	s_waitcnt lgkmcnt(1)
	v_mfma_f32_16x16x32_bf16 v[168:171], v[70:73], v[66:69], v[172:175]
	ds_read_b128 v[66:69], v159 offset:38912
	s_waitcnt lgkmcnt(1)
	v_mfma_f32_16x16x32_bf16 v[172:175], v[70:73], v[240:243], v[176:179]
	ds_read_b128 v[240:243], v159 offset:43008
	s_waitcnt lgkmcnt(1)
	v_mfma_f32_16x16x32_bf16 v[70:73], v[78:81], v[66:69], v[74:77]
	ds_read_b128 v[66:69], v159 offset:47104
	s_waitcnt lgkmcnt(1)
	v_mfma_f32_16x16x32_bf16 v[74:77], v[78:81], v[240:243], v[164:167]
	ds_read_b128 v[240:243], v159 offset:51200
	s_waitcnt lgkmcnt(1)
	v_mfma_f32_16x16x32_bf16 v[164:167], v[78:81], v[66:69], v[168:171]
	ds_read_b128 v[66:69], v159 offset:39936
	s_waitcnt lgkmcnt(1)
	v_mfma_f32_16x16x32_bf16 v[168:171], v[78:81], v[240:243], v[172:175]
	ds_read_b128 v[240:243], v159 offset:44032
	s_waitcnt lgkmcnt(1)
	v_mfma_f32_16x16x32_bf16 v[70:73], v[160:163], v[66:69], v[70:73]
	ds_read_b128 v[66:69], v159 offset:48128
	s_waitcnt lgkmcnt(1)
	v_mfma_f32_16x16x32_bf16 v[74:77], v[160:163], v[240:243], v[74:77]
	ds_read_b128 v[240:243], v159 offset:52224
	s_waitcnt lgkmcnt(1)
	v_mfma_f32_16x16x32_bf16 v[78:81], v[160:163], v[66:69], v[164:167]
	s_waitcnt lgkmcnt(0)
	v_mfma_f32_16x16x32_bf16 v[164:167], v[160:163], v[240:243], v[168:171]
	s_nop 15
	s_add_i32 s27, s1, s2
	v_pk_mul_f32 v[66:67], v[70:71], s[0:1] op_sel_hi:[1,0]
	v_pk_mul_f32 v[68:69], v[72:73], s[0:1] op_sel_hi:[1,0]
	v_cvt_pk_bf16_f32 v66, v66, v67
	v_cvt_pk_bf16_f32 v67, v68, v69
	ds_write_b64 v140, v[66:67] offset:32
	v_pk_mul_f32 v[66:67], v[74:75], s[0:1] op_sel_hi:[1,0]
	v_pk_mul_f32 v[68:69], v[76:77], s[0:1] op_sel_hi:[1,0]
	v_cvt_pk_bf16_f32 v66, v66, v67
	v_cvt_pk_bf16_f32 v67, v68, v69
	ds_write_b64 v140, v[66:67] offset:8480
	v_pk_mul_f32 v[66:67], v[78:79], s[0:1] op_sel_hi:[1,0]
	v_pk_mul_f32 v[68:69], v[80:81], s[0:1] op_sel_hi:[1,0]
	s_cmpk_lt_i32 s27, 0x200
	v_cvt_pk_bf16_f32 v66, v66, v67
	v_cvt_pk_bf16_f32 v67, v68, v69
	s_cselect_b64 s[18:19], -1, 0
	s_cmpk_gt_i32 s27, 0x1ff
	ds_write_b64 v140, v[66:67] offset:16928
	v_pk_mul_f32 v[66:67], v[164:165], s[0:1] op_sel_hi:[1,0]
	v_pk_mul_f32 v[68:69], v[166:167], s[0:1] op_sel_hi:[1,0]
	s_cselect_b64 s[6:7], -1, 0
	v_cvt_pk_bf16_f32 v66, v66, v67
	v_cvt_pk_bf16_f32 v67, v68, v69
	s_and_b64 vcc, exec, s[6:7]
	ds_write_b64 v140, v[66:67] offset:25376
	s_cbranch_vccnz .LBB0_2530
	s_lshr_b32 s3, s27, 4
	s_and_b32 s3, s3, 0x3fffffc
	s_add_i32 s3, s3, s25
	s_lshl_b32 s3, s3, 6
	s_and_b32 s28, s27, 63
	s_or_b32 s28, s3, s28
	s_ashr_i32 s29, s28, 31
	s_lshl_b64 s[28:29], s[28:29], 14
	s_add_u32 s28, s21, s28
	s_addc_u32 s29, s23, s29
	global_load_dword v101, v141, s[28:29]
	global_load_dword v105, v141, s[28:29] offset:256
	global_load_dword v107, v141, s[28:29] offset:512
	global_load_dword v109, v141, s[28:29] offset:768
	global_load_dword v112, v141, s[28:29] offset:1024
	global_load_dword v113, v141, s[28:29] offset:1280
	global_load_dword v114, v141, s[28:29] offset:1536
	global_load_dword v115, v141, s[28:29] offset:64
	global_load_dword v116, v141, s[28:29] offset:1792
	global_load_dword v117, v142, s[28:29]
	global_load_dword v118, v143, s[28:29]
	global_load_dword v120, v144, s[28:29]
	global_load_dword v121, v145, s[28:29]
	global_load_dword v119, v144, s[28:29] offset:64
	global_load_dword v122, v143, s[28:29] offset:64
	global_load_dword v123, v142, s[28:29] offset:64
	global_load_dword v126, v146, s[28:29]
	global_load_dword v127, v147, s[28:29]
	global_load_dword v129, v148, s[28:29]
	global_load_dword v130, v149, s[28:29]
	global_load_dword v124, v148, s[28:29] offset:64
	global_load_dword v125, v147, s[28:29] offset:64
	global_load_dword v128, v146, s[28:29] offset:64
	global_load_dword v131, v145, s[28:29] offset:64
	global_load_dword v133, v150, s[28:29] offset:64
	global_load_dword v134, v151, s[28:29] offset:64
	global_load_dword v135, v152, s[28:29] offset:64
	global_load_dword v136, v153, s[28:29] offset:64
	global_load_dword v137, v154, s[28:29] offset:64
	global_load_dword v138, v155, s[28:29] offset:64
	global_load_dword v139, v156, s[28:29] offset:64
	global_load_dword v132, v149, s[28:29] offset:64
